# v24 + same first-trip peel (C=0, no accumulator zeroing) in the gated-branch gemm_multi K-loop (sub 11)
# speedup vs baseline: 1.0123x; 1.0039x over previous
; #define PG8_STAGE(bufoff, gbase, voff) do { _Pragma("unroll") for (int _i = 0; _i < 2; ++_i) \
;         __builtin_amdgcn_global_load_lds((const unsigned*)((const char*)(gbase) + (voff)[_i]), (LAS unsigned*)(lds + (bufoff) + ldsw + _i * 8192), 16, 0, 0); } while (0)
; #define PG8_LDA(dst, b, h) do { _Pragma("unroll") for (int m = 0; m < 4; ++m) _Pragma("unroll") for (int k = 0; k < 2; ++k) dst[m][k] = *(const LAS bf16x8*)(lds + PG8_SA(b, h) + aoff + m * 2048 + k * 1024); } while (0)
; #define PG8_LDB(dst, b, h) do { _Pragma("unroll") for (int n = 0; n < 2; ++n) _Pragma("unroll") for (int k = 0; k < 2; ++k) dst[n][k] = *(const LAS bf16x8*)(lds + PG8_SB(b, h) + boff + n * 2048 + k * 1024); } while (0)
; #define PG8_MMA(ai, bj, At, Bt) do { __builtin_amdgcn_s_setprio(1); _Pragma("unroll") for (int m = 0; m < 4; ++m) _Pragma("unroll") for (int n = 0; n < 2; ++n) _Pragma("unroll") for (int k = 0; k < 2; ++k) \
;         acc[ai][bj][m][n] = __builtin_amdgcn_mfma_f32_16x16x32_bf16(Bt[n][k], At[m][k], acc[ai][bj][m][n], 0, 0, 0); __builtin_amdgcn_s_setprio(0); } while (0)
; #define PG8_BAR __builtin_amdgcn_s_barrier()
; template <class Epi, class Sched, class GSel>
; __device__ __forceinline__ void gemm_multi(LAS unsigned char* lds, const GSel GS, const Sched S, const Epi E, const int tid) {
;     ...
;         const Gemm gn = GS.get(nxt.kind);
;         unsigned vAn, vBn; PGM_VOFF(vAn, vBn, gn);
;         const size_t hAn = (size_t)HALF * gn.lda * 2, hBn = (size_t)HALF * gn.ldb * 2;
;         const char* nA = (const char*)gn.A + (size_t)nxt.pm * 2 * hAn; const char* nB = (const char*)gn.Bt + (size_t)nxt.pn * 2 * hBn;
;         for (int t = 0; t < ntc; t += 2) {
;             const bool last = (t == ntc - 2);
;             const char* a1 = cA + (size_t)(t + 1) * kstep;
;             const char* a2 = last ? nA : cA + (size_t)(t + 2) * kstep; const char* b2 = last ? nB : cB + (size_t)(t + 2) * kstep;
;             const char* a3 = a2 + kstep; const char* b3 = b2 + kstep;
;             const unsigned vA2 = last ? vAn : vAc, vB2 = last ? vBn : vBc;
;             const size_t hA2 = last ? hAn : hAc, hB2 = last ? hBn : hBc;
;             PG8_LDB(B0, 0, 0); PG8_LDB(B1, 0, 1); PG8_SCHED; PG8_LDA(At, 0, 0); PG8_STAGE(PG8_SA(1, 1), a1 + hAc, vAc, hAc / 2);
;             PG8_WAIT_V(8); PG8_WAIT_L(0); PG8_BAR; PG8_MMA(0, 0, At, B0); PG8_MMA(0, 1, At, B1); PG8_BAR; PG8_SCHED;
.LBB0_880:
	s_add_u32 s15, s38, s28
	s_addc_u32 s23, s39, s29
	v_readlane_b32 s18, v254, 52
	v_readlane_b32 s19, v254, 53
	s_add_u32 s26, s18, s26
	s_addc_u32 s27, s19, s27
	s_ashr_i32 s21, s20, 31
	s_lshl_b64 s[18:19], s[20:21], s22
	s_add_u32 s20, s26, s18
	s_addc_u32 s21, s27, s19
	s_lshl_b32 s92, s75, 8
	s_mul_hi_i32 s19, s73, s92
	s_mul_i32 s18, s73, s92
	s_lshl_b64 s[18:19], s[18:19], 1
	s_add_u32 s48, s15, s18
	s_addc_u32 s49, s23, s19
	s_mul_hi_i32 s19, s72, s92
	s_mul_i32 s18, s72, s92
	s_lshl_b64 s[18:19], s[18:19], 1
	v_mul_lo_u32 v2, s75, v150
	s_add_u32 s50, s20, s18
	v_add_lshl_u32 v130, v2, v151, 1
	v_mul_lo_u32 v2, s75, v152
	s_addc_u32 s51, s21, s19
	s_cmp_lt_i32 s14, 1
	v_add_lshl_u32 v157, v2, v151, 1
	s_cbranch_scc1 .LBB0_990
	s_add_i32 s15, s14, -2
	s_lshr_b64 s[20:21], s[16:17], 1
	s_lshr_b32 s22, s92, 1
	s_add_u32 s18, s24, 0x100
	s_addc_u32 s19, s25, 0
	s_add_u32 s24, s16, s20
	s_addc_u32 s25, s17, s21
	s_add_u32 s24, s4, s24
	s_addc_u32 s25, s5, s25
	v_lshl_add_u64 v[2:3], s[24:25], 0, v[0:1]
	s_add_u32 s24, s4, s16
	v_lshl_add_u64 v[136:137], v[2:3], 0, s[0:1]
	s_addc_u32 s25, s5, s17
	v_mov_b32_e32 v2, 0
	s_mov_b64 s[38:39], s[60:61]
	v_mov_b64_e32 v[134:135], v[0:1]
	v_mov_b32_e32 v131, v1
	s_mov_b32 s23, s93
	v_lshl_add_u64 v[138:139], s[24:25], 0, v[0:1]
	s_mov_b32 s31, 0
	s_mov_b64 s[24:25], 0
	s_cmp_eq_u32 s15, s31
	s_cselect_b64 s[60:61], -1, 0
	s_and_b64 vcc, exec, s[60:61]
	s_mov_b64 s[26:27], s[22:23]
	v_mov_b64_e32 v[140:141], v[130:131]
	s_mov_b64 s[28:29], s[92:93]
	v_mov_b32_e32 v0, v157
	s_mov_b64 s[52:53], s[50:51]
	s_cbranch_vccnz .Lpm882_body
	s_add_u32 s52, s18, s24
	s_addc_u32 s53, s19, s25
	s_mov_b64 s[26:27], s[20:21]
	v_mov_b64_e32 v[140:141], v[134:135]
	s_mov_b64 s[28:29], s[16:17]
	v_mov_b32_e32 v0, v132
	s_branch .Lpm882_body
.Lpm882_body:
	s_add_i32 s31, s31, 2
	s_add_u32 s34, s4, s24
	s_addc_u32 s35, s5, s25
	s_add_u32 s36, s34, 0x100
	s_addc_u32 s37, s35, 0
	s_and_b64 s[34:35], exec, s[60:61]
	s_cselect_b32 s61, s49, s37
	s_cselect_b32 s60, s48, s36
	s_add_i32 s34, 0, 0x10000
	v_add_u32_e32 v133, s34, v155
	s_add_i32 s36, 0, 0x14000
	ds_read_b128 v[142:145], v133
	ds_read_b128 v[146:149], v133 offset:1024
	ds_read_b128 v[158:161], v133 offset:2048
	ds_read_b128 v[162:165], v133 offset:3072
	v_add_u32_e32 v133, s36, v155
	ds_read_b128 v[166:169], v133
	ds_read_b128 v[170:173], v133 offset:1024
	ds_read_b128 v[174:177], v133 offset:2048
	ds_read_b128 v[178:181], v133 offset:3072
	v_lshl_add_u64 v[190:191], v[138:139], 0, s[24:25]
	v_lshl_add_u64 v[190:191], v[190:191], 0, s[0:1]
	s_add_i32 m0, s64, 0xc000
	ds_read_b128 v[182:185], v156
	ds_read_b128 v[186:189], v156 offset:1024
	ds_read_b128 v[206:209], v156 offset:2048
	ds_read_b128 v[218:221], v156 offset:3072
	ds_read_b128 v[232:235], v156 offset:4096
	ds_read_b128 v[236:239], v156 offset:5120
	ds_read_b128 v[240:243], v156 offset:6144
	ds_read_b128 v[244:247], v156 offset:7168
	global_load_lds_dwordx4 v[190:191], off
	v_lshl_add_u64 v[190:191], v[136:137], 0, s[24:25]
	s_add_i32 m0, s64, 0xe000
	s_nop 0
	global_load_lds_dwordx4 v[190:191], off
	s_waitcnt vmcnt(8)
	s_waitcnt lgkmcnt(0)
	s_barrier
	s_setprio 1
	s_waitcnt lgkmcnt(0)
	v_mfma_f32_16x16x32_bf16 v[126:129], v[142:145], v[182:185], 0
	v_mfma_f32_16x16x32_bf16 v[122:125], v[158:161], v[182:185], 0
	v_mfma_f32_16x16x32_bf16 v[110:113], v[142:145], v[206:209], 0
	v_mfma_f32_16x16x32_bf16 v[106:109], v[158:161], v[206:209], 0
	v_mfma_f32_16x16x32_bf16 v[94:97], v[142:145], v[232:235], 0
	v_mfma_f32_16x16x32_bf16 v[90:93], v[158:161], v[232:235], 0
	v_mfma_f32_16x16x32_bf16 v[78:81], v[142:145], v[240:243], 0
	v_mfma_f32_16x16x32_bf16 v[74:77], v[158:161], v[240:243], 0
	v_mfma_f32_16x16x32_bf16 v[126:129], v[146:149], v[186:189], v[126:129]
	v_mfma_f32_16x16x32_bf16 v[122:125], v[162:165], v[186:189], v[122:125]
	v_mfma_f32_16x16x32_bf16 v[110:113], v[146:149], v[218:221], v[110:113]
	v_mfma_f32_16x16x32_bf16 v[106:109], v[162:165], v[218:221], v[106:109]
	v_mfma_f32_16x16x32_bf16 v[94:97], v[146:149], v[236:239], v[94:97]
	v_mfma_f32_16x16x32_bf16 v[90:93], v[162:165], v[236:239], v[90:93]
	v_mfma_f32_16x16x32_bf16 v[78:81], v[146:149], v[244:247], v[78:81]
	v_mfma_f32_16x16x32_bf16 v[74:77], v[162:165], v[244:247], v[74:77]
	s_setprio 0
	s_setprio 1
	v_mfma_f32_16x16x32_bf16 v[118:121], v[166:169], v[182:185], 0
	v_mfma_f32_16x16x32_bf16 v[114:117], v[174:177], v[182:185], 0
	v_mfma_f32_16x16x32_bf16 v[102:105], v[166:169], v[206:209], 0
	v_mfma_f32_16x16x32_bf16 v[98:101], v[174:177], v[206:209], 0
	v_mfma_f32_16x16x32_bf16 v[86:89], v[166:169], v[232:235], 0
	v_mfma_f32_16x16x32_bf16 v[82:85], v[174:177], v[232:235], 0
	v_mfma_f32_16x16x32_bf16 v[70:73], v[166:169], v[240:243], 0
	v_mfma_f32_16x16x32_bf16 v[66:69], v[174:177], v[240:243], 0
	v_mfma_f32_16x16x32_bf16 v[118:121], v[170:173], v[186:189], v[118:121]
	v_mfma_f32_16x16x32_bf16 v[114:117], v[178:181], v[186:189], v[114:117]
	v_mfma_f32_16x16x32_bf16 v[102:105], v[170:173], v[218:221], v[102:105]
	v_mfma_f32_16x16x32_bf16 v[98:101], v[178:181], v[218:221], v[98:101]
	v_mfma_f32_16x16x32_bf16 v[86:89], v[170:173], v[236:239], v[86:89]
	v_mfma_f32_16x16x32_bf16 v[82:85], v[178:181], v[236:239], v[82:85]
	v_mfma_f32_16x16x32_bf16 v[70:73], v[170:173], v[244:247], v[70:73]
	v_mfma_f32_16x16x32_bf16 v[66:69], v[178:181], v[244:247], v[66:69]
	s_setprio 0
	s_barrier
; #define PG8_STAGE(bufoff, gbase, voff) do { _Pragma("unroll") for (int _i = 0; _i < 2; ++_i) \
;         __builtin_amdgcn_global_load_lds((const unsigned*)((const char*)(gbase) + (voff)[_i]), (LAS unsigned*)(lds + (bufoff) + ldsw + _i * 8192), 16, 0, 0); } while (0)
; #define PG8_LDA(dst, b, h) do { _Pragma("unroll") for (int m = 0; m < 4; ++m) _Pragma("unroll") for (int k = 0; k < 2; ++k) dst[m][k] = *(const LAS bf16x8*)(lds + PG8_SA(b, h) + aoff + m * 2048 + k * 1024); } while (0)
; #define PG8_LDB(dst, b, h) do { _Pragma("unroll") for (int n = 0; n < 2; ++n) _Pragma("unroll") for (int k = 0; k < 2; ++k) dst[n][k] = *(const LAS bf16x8*)(lds + PG8_SB(b, h) + boff + n * 2048 + k * 1024); } while (0)
; #define PG8_MMA(ai, bj, At, Bt) do { __builtin_amdgcn_s_setprio(1); _Pragma("unroll") for (int m = 0; m < 4; ++m) _Pragma("unroll") for (int n = 0; n < 2; ++n) _Pragma("unroll") for (int k = 0; k < 2; ++k) \
;         acc[ai][bj][m][n] = __builtin_amdgcn_mfma_f32_16x16x32_bf16(Bt[n][k], At[m][k], acc[ai][bj][m][n], 0, 0, 0); __builtin_amdgcn_s_setprio(0); } while (0)
; #define PG8_WAIT_V(n) asm volatile("s_waitcnt vmcnt(" #n ")" ::: "memory")
; #define PG8_WAIT_L(n) asm volatile("s_waitcnt lgkmcnt(" #n ")" ::: "memory")
; #define PG8_BAR __builtin_amdgcn_s_barrier()
; #define PG8_SCHED __builtin_amdgcn_sched_barrier(0)
; #define PG8_WAIT_V(n) asm volatile("s_waitcnt vmcnt(" #n ")" ::: "memory")
; #define PG8_WAIT_L(n) asm volatile("s_waitcnt lgkmcnt(" #n ")" ::: "memory")
; template <class Epi, class Sched, class GSel>
; __device__ __forceinline__ void gemm_multi(LAS unsigned char* lds, const GSel GS, const Sched S, const Epi E, const int tid) {
;     ...
;             PG8_LDA(At, 0, 1); PG8_STAGE(PG8_SB(0, 0), b2, vB2, hB2 / 2); PG8_STAGE(PG8_SB(0, 1), b2 + hB2, vB2, hB2 / 2); PG8_STAGE(PG8_SA(0, 0), a2, vA2, hA2 / 2);
;             PG8_WAIT_V(8); PG8_WAIT_L(0); PG8_BAR; PG8_MMA(1, 0, At, B0); PG8_MMA(1, 1, At, B1); PG8_BAR; PG8_SCHED;
;             PG8_LDB(B0, 1, 0); PG8_LDB(B1, 1, 1); PG8_SCHED; PG8_LDA(At, 1, 0); PG8_STAGE(PG8_SA(0, 1), a2 + hA2, vA2, hA2 / 2);
;             PG8_WAIT_V(8); PG8_WAIT_L(0); PG8_BAR; PG8_MMA(0, 0, At, B0); PG8_MMA(0, 1, At, B1); PG8_BAR; PG8_SCHED;
;             PG8_LDA(At, 1, 1); PG8_STAGE(PG8_SB(1, 0), b3, vB2, hB2 / 2); PG8_STAGE(PG8_SB(1, 1), b3 + hB2, vB2, hB2 / 2); PG8_STAGE(PG8_SA(1, 0), a3, vA2, hA2 / 2);
	s_add_i32 s37, s34, s63
	s_mov_b32 m0, s37
	s_add_u32 s34, s52, s26
	ds_read_b128 v[182:185], v156 offset:16384
	ds_read_b128 v[186:189], v156 offset:17408
	ds_read_b128 v[206:209], v156 offset:18432
	ds_read_b128 v[218:221], v156 offset:19456
	ds_read_b128 v[232:235], v156 offset:20480
	ds_read_b128 v[236:239], v156 offset:21504
	ds_read_b128 v[240:243], v156 offset:22528
	ds_read_b128 v[244:247], v156 offset:23552
	global_load_lds_dwordx4 v0, s[52:53]
	s_addc_u32 s35, s53, s27
	s_add_i32 m0, s37, 0x2000
	v_lshl_add_u64 v[192:193], s[34:35], 0, v[0:1]
	global_load_lds_dwordx4 v0, s[34:35]
	s_add_u32 s34, s52, s28
	s_addc_u32 s35, s53, s29
	s_add_i32 s36, s36, s63
	s_mov_b32 m0, s36
	v_lshl_add_u64 v[194:195], s[34:35], 0, v[0:1]
	global_load_lds_dwordx4 v0, s[34:35]
	s_add_u32 s34, s34, s26
	s_addc_u32 s35, s35, s27
	s_add_i32 m0, s36, 0x2000
	v_lshl_add_u64 v[210:211], s[34:35], 0, v[0:1]
	global_load_lds_dwordx4 v0, s[34:35]
	s_add_u32 s34, s60, s26
	v_lshl_add_u64 v[222:223], s[60:61], 0, v[140:141]
	s_mov_b32 m0, s64
	s_addc_u32 s35, s61, s27
	global_load_lds_dwordx4 v[222:223], off
	v_lshl_add_u64 v[248:249], s[34:35], 0, v[140:141]
	s_mov_b32 m0, s65
	v_lshl_add_u64 v[190:191], s[52:53], 0, v[0:1]
	global_load_lds_dwordx4 v[248:249], off
	s_waitcnt vmcnt(8)
	s_waitcnt lgkmcnt(0)
	s_barrier
	s_setprio 1
	s_waitcnt lgkmcnt(0)
	v_mfma_f32_16x16x32_bf16 v[62:65], v[142:145], v[182:185], 0
	v_mfma_f32_16x16x32_bf16 v[58:61], v[158:161], v[182:185], 0
	v_mfma_f32_16x16x32_bf16 v[46:49], v[142:145], v[206:209], 0
	v_mfma_f32_16x16x32_bf16 v[42:45], v[158:161], v[206:209], 0
	v_mfma_f32_16x16x32_bf16 v[30:33], v[142:145], v[232:235], 0
	v_mfma_f32_16x16x32_bf16 v[26:29], v[158:161], v[232:235], 0
	v_mfma_f32_16x16x32_bf16 v[14:17], v[142:145], v[240:243], 0
	v_mfma_f32_16x16x32_bf16 v[10:13], v[158:161], v[240:243], 0
	v_mfma_f32_16x16x32_bf16 v[62:65], v[146:149], v[186:189], v[62:65]
	v_mfma_f32_16x16x32_bf16 v[58:61], v[162:165], v[186:189], v[58:61]
	v_mfma_f32_16x16x32_bf16 v[46:49], v[146:149], v[218:221], v[46:49]
	v_mfma_f32_16x16x32_bf16 v[42:45], v[162:165], v[218:221], v[42:45]
	v_mfma_f32_16x16x32_bf16 v[30:33], v[146:149], v[236:239], v[30:33]
	v_mfma_f32_16x16x32_bf16 v[26:29], v[162:165], v[236:239], v[26:29]
	v_mfma_f32_16x16x32_bf16 v[14:17], v[146:149], v[244:247], v[14:17]
	v_mfma_f32_16x16x32_bf16 v[10:13], v[162:165], v[244:247], v[10:13]
	s_setprio 0
	s_setprio 1
	v_mfma_f32_16x16x32_bf16 v[54:57], v[166:169], v[182:185], 0
	v_mfma_f32_16x16x32_bf16 v[50:53], v[174:177], v[182:185], 0
	v_mfma_f32_16x16x32_bf16 v[38:41], v[166:169], v[206:209], 0
	v_mfma_f32_16x16x32_bf16 v[34:37], v[174:177], v[206:209], 0
	v_mfma_f32_16x16x32_bf16 v[22:25], v[166:169], v[232:235], 0
	v_mfma_f32_16x16x32_bf16 v[18:21], v[174:177], v[232:235], 0
	v_mfma_f32_16x16x32_bf16 v[6:9], v[166:169], v[240:243], 0
	v_mfma_f32_16x16x32_bf16 v[2:5], v[174:177], v[240:243], 0
	v_mfma_f32_16x16x32_bf16 v[54:57], v[170:173], v[186:189], v[54:57]
	v_mfma_f32_16x16x32_bf16 v[50:53], v[178:181], v[186:189], v[50:53]
	v_mfma_f32_16x16x32_bf16 v[38:41], v[170:173], v[218:221], v[38:41]
	v_mfma_f32_16x16x32_bf16 v[34:37], v[178:181], v[218:221], v[34:37]
	v_mfma_f32_16x16x32_bf16 v[22:25], v[170:173], v[236:239], v[22:25]
	v_mfma_f32_16x16x32_bf16 v[18:21], v[178:181], v[236:239], v[18:21]
	v_mfma_f32_16x16x32_bf16 v[6:9], v[170:173], v[244:247], v[6:9]
	v_mfma_f32_16x16x32_bf16 v[2:5], v[178:181], v[244:247], v[2:5]
	s_setprio 0
	s_barrier
	s_add_i32 s34, 0, 0x18000
	v_add_u32_e32 v0, s34, v155
	s_add_i32 s35, 0, 0x1c000
	ds_read_b128 v[142:145], v0
	ds_read_b128 v[146:149], v0 offset:1024
	ds_read_b128 v[158:161], v0 offset:2048
	ds_read_b128 v[162:165], v0 offset:3072
	v_add_u32_e32 v0, s35, v155
	ds_read_b128 v[166:169], v0
	ds_read_b128 v[170:173], v0 offset:1024
	ds_read_b128 v[174:177], v0 offset:2048
	ds_read_b128 v[178:181], v0 offset:3072
	s_add_u32 s28, s60, s28
	s_addc_u32 s29, s61, s29
	s_add_u32 s26, s28, s26
	s_mov_b32 m0, s66
	v_lshl_add_u64 v[250:251], s[28:29], 0, v[140:141]
	s_addc_u32 s27, s29, s27
	ds_read_b128 v[182:185], v156 offset:32768
	ds_read_b128 v[186:189], v156 offset:33792
	ds_read_b128 v[206:209], v156 offset:34816
	ds_read_b128 v[218:221], v156 offset:35840
	ds_read_b128 v[232:235], v156 offset:36864
	ds_read_b128 v[236:239], v156 offset:37888
	ds_read_b128 v[240:243], v156 offset:38912
	ds_read_b128 v[244:247], v156 offset:39936
	global_load_lds_dwordx4 v[250:251], off
	v_lshl_add_u64 v[140:141], s[26:27], 0, v[140:141]
	s_mov_b32 m0, s67
	s_nop 0
	global_load_lds_dwordx4 v[140:141], off
	s_waitcnt vmcnt(8)
	s_waitcnt lgkmcnt(0)
	s_barrier
; #define PG8_STAGE(bufoff, gbase, voff) do { _Pragma("unroll") for (int _i = 0; _i < 2; ++_i) \
;         __builtin_amdgcn_global_load_lds((const unsigned*)((const char*)(gbase) + (voff)[_i]), (LAS unsigned*)(lds + (bufoff) + ldsw + _i * 8192), 16, 0, 0); } while (0)
; #define PG8_LDA(dst, b, h) do { _Pragma("unroll") for (int m = 0; m < 4; ++m) _Pragma("unroll") for (int k = 0; k < 2; ++k) dst[m][k] = *(const LAS bf16x8*)(lds + PG8_SA(b, h) + aoff + m * 2048 + k * 1024); } while (0)
; #define PG8_LDB(dst, b, h) do { _Pragma("unroll") for (int n = 0; n < 2; ++n) _Pragma("unroll") for (int k = 0; k < 2; ++k) dst[n][k] = *(const LAS bf16x8*)(lds + PG8_SB(b, h) + boff + n * 2048 + k * 1024); } while (0)
; #define PG8_MMA(ai, bj, At, Bt) do { __builtin_amdgcn_s_setprio(1); _Pragma("unroll") for (int m = 0; m < 4; ++m) _Pragma("unroll") for (int n = 0; n < 2; ++n) _Pragma("unroll") for (int k = 0; k < 2; ++k) \
;         acc[ai][bj][m][n] = __builtin_amdgcn_mfma_f32_16x16x32_bf16(Bt[n][k], At[m][k], acc[ai][bj][m][n], 0, 0, 0); __builtin_amdgcn_s_setprio(0); } while (0)
; #define PG8_WAIT_V(n) asm volatile("s_waitcnt vmcnt(" #n ")" ::: "memory")
; #define PG8_WAIT_L(n) asm volatile("s_waitcnt lgkmcnt(" #n ")" ::: "memory")
; #define PG8_BAR __builtin_amdgcn_s_barrier()
; #define PG8_SCHED __builtin_amdgcn_sched_barrier(0)
; #define PG8_LDA(dst, b, h) do { _Pragma("unroll") for (int m = 0; m < 4; ++m) _Pragma("unroll") for (int k = 0; k < 2; ++k) dst[m][k] = *(const LAS bf16x8*)(lds + PG8_SA(b, h) + aoff + m * 2048 + k * 1024); } while (0)
; #define PG8_WAIT_V(n) asm volatile("s_waitcnt vmcnt(" #n ")" ::: "memory")
; template <class Epi, class Sched, class GSel>
; __device__ __forceinline__ void gemm_multi(LAS unsigned char* lds, const GSel GS, const Sched S, const Epi E, const int tid) {
;     ...
;             PG8_LDB(B0, 1, 0); PG8_LDB(B1, 1, 1); PG8_SCHED; PG8_LDA(At, 1, 0); PG8_STAGE(PG8_SA(0, 1), a2 + hA2, vA2, hA2 / 2);
;             PG8_WAIT_V(8); PG8_WAIT_L(0); PG8_BAR; PG8_MMA(0, 0, At, B0); PG8_MMA(0, 1, At, B1); PG8_BAR; PG8_SCHED;
;             PG8_LDA(At, 1, 1); PG8_STAGE(PG8_SB(1, 0), b3, vB2, hB2 / 2); PG8_STAGE(PG8_SB(1, 1), b3 + hB2, vB2, hB2 / 2); PG8_STAGE(PG8_SA(1, 0), a3, vA2, hA2 / 2);
;             PG8_WAIT_V(8); PG8_WAIT_L(0); PG8_BAR; PG8_MMA(1, 0, At, B0); PG8_MMA(1, 1, At, B1); PG8_BAR; PG8_SCHED;
;         }
	s_setprio 1
	s_waitcnt lgkmcnt(0)
	v_mfma_f32_16x16x32_bf16 v[126:129], v[142:145], v[182:185], v[126:129]
	v_mfma_f32_16x16x32_bf16 v[122:125], v[158:161], v[182:185], v[122:125]
	v_mfma_f32_16x16x32_bf16 v[110:113], v[142:145], v[206:209], v[110:113]
	v_mfma_f32_16x16x32_bf16 v[106:109], v[158:161], v[206:209], v[106:109]
	v_mfma_f32_16x16x32_bf16 v[94:97], v[142:145], v[232:235], v[94:97]
	v_mfma_f32_16x16x32_bf16 v[90:93], v[158:161], v[232:235], v[90:93]
	v_mfma_f32_16x16x32_bf16 v[78:81], v[142:145], v[240:243], v[78:81]
	v_mfma_f32_16x16x32_bf16 v[74:77], v[158:161], v[240:243], v[74:77]
	v_mfma_f32_16x16x32_bf16 v[126:129], v[146:149], v[186:189], v[126:129]
	v_mfma_f32_16x16x32_bf16 v[122:125], v[162:165], v[186:189], v[122:125]
	v_mfma_f32_16x16x32_bf16 v[110:113], v[146:149], v[218:221], v[110:113]
	v_mfma_f32_16x16x32_bf16 v[106:109], v[162:165], v[218:221], v[106:109]
	v_mfma_f32_16x16x32_bf16 v[94:97], v[146:149], v[236:239], v[94:97]
	v_mfma_f32_16x16x32_bf16 v[90:93], v[162:165], v[236:239], v[90:93]
	v_mfma_f32_16x16x32_bf16 v[78:81], v[146:149], v[244:247], v[78:81]
	v_mfma_f32_16x16x32_bf16 v[74:77], v[162:165], v[244:247], v[74:77]
	s_setprio 0
	s_setprio 1
	v_mfma_f32_16x16x32_bf16 v[118:121], v[166:169], v[182:185], v[118:121]
	v_mfma_f32_16x16x32_bf16 v[114:117], v[174:177], v[182:185], v[114:117]
	v_mfma_f32_16x16x32_bf16 v[102:105], v[166:169], v[206:209], v[102:105]
	v_mfma_f32_16x16x32_bf16 v[98:101], v[174:177], v[206:209], v[98:101]
	v_mfma_f32_16x16x32_bf16 v[86:89], v[166:169], v[232:235], v[86:89]
	v_mfma_f32_16x16x32_bf16 v[82:85], v[174:177], v[232:235], v[82:85]
	v_mfma_f32_16x16x32_bf16 v[70:73], v[166:169], v[240:243], v[70:73]
	v_mfma_f32_16x16x32_bf16 v[66:69], v[174:177], v[240:243], v[66:69]
	v_mfma_f32_16x16x32_bf16 v[118:121], v[170:173], v[186:189], v[118:121]
	v_mfma_f32_16x16x32_bf16 v[114:117], v[178:181], v[186:189], v[114:117]
	v_mfma_f32_16x16x32_bf16 v[102:105], v[170:173], v[218:221], v[102:105]
	v_mfma_f32_16x16x32_bf16 v[98:101], v[178:181], v[218:221], v[98:101]
	v_mfma_f32_16x16x32_bf16 v[86:89], v[170:173], v[236:239], v[86:89]
	v_mfma_f32_16x16x32_bf16 v[82:85], v[178:181], v[236:239], v[82:85]
	v_mfma_f32_16x16x32_bf16 v[70:73], v[170:173], v[244:247], v[70:73]
	v_mfma_f32_16x16x32_bf16 v[66:69], v[178:181], v[244:247], v[66:69]
	s_setprio 0
	s_barrier
	s_add_i32 s26, s34, s63
	v_lshl_add_u64 v[140:141], v[190:191], 0, s[0:1]
	s_mov_b32 m0, s26
	ds_read_b128 v[182:185], v156 offset:49152
	ds_read_b128 v[186:189], v156 offset:50176
	ds_read_b128 v[206:209], v156 offset:51200
	ds_read_b128 v[218:221], v156 offset:52224
	ds_read_b128 v[232:235], v156 offset:53248
	ds_read_b128 v[236:239], v156 offset:54272
	ds_read_b128 v[240:243], v156 offset:55296
	ds_read_b128 v[244:247], v156 offset:56320
	global_load_lds_dwordx4 v[140:141], off
	v_lshl_add_u64 v[140:141], v[192:193], 0, s[0:1]
	s_add_i32 m0, s26, 0x2000
	s_add_i32 s26, s35, s63
	global_load_lds_dwordx4 v[140:141], off
	v_lshl_add_u64 v[140:141], v[194:195], 0, s[0:1]
	s_mov_b32 m0, s26
	s_nop 0
	global_load_lds_dwordx4 v[140:141], off
	v_lshl_add_u64 v[140:141], v[210:211], 0, s[0:1]
	s_add_i32 m0, s26, 0x2000
	s_nop 0
	global_load_lds_dwordx4 v[140:141], off
	v_lshl_add_u64 v[140:141], v[222:223], 0, s[0:1]
	s_mov_b32 m0, s69
	s_nop 0
	global_load_lds_dwordx4 v[140:141], off
	v_lshl_add_u64 v[140:141], v[248:249], 0, s[0:1]
	s_mov_b32 m0, s70
	s_nop 0
	global_load_lds_dwordx4 v[140:141], off
	s_waitcnt vmcnt(8)
	s_waitcnt lgkmcnt(0)
	s_barrier
	s_setprio 1
	s_waitcnt lgkmcnt(0)
	v_mfma_f32_16x16x32_bf16 v[62:65], v[142:145], v[182:185], v[62:65]
	v_mfma_f32_16x16x32_bf16 v[58:61], v[158:161], v[182:185], v[58:61]
	v_mfma_f32_16x16x32_bf16 v[46:49], v[142:145], v[206:209], v[46:49]
	v_mfma_f32_16x16x32_bf16 v[42:45], v[158:161], v[206:209], v[42:45]
	v_mfma_f32_16x16x32_bf16 v[30:33], v[142:145], v[232:235], v[30:33]
	v_mfma_f32_16x16x32_bf16 v[26:29], v[158:161], v[232:235], v[26:29]
	v_mfma_f32_16x16x32_bf16 v[14:17], v[142:145], v[240:243], v[14:17]
	v_mfma_f32_16x16x32_bf16 v[10:13], v[158:161], v[240:243], v[10:13]
	v_mfma_f32_16x16x32_bf16 v[62:65], v[146:149], v[186:189], v[62:65]
	v_mfma_f32_16x16x32_bf16 v[58:61], v[162:165], v[186:189], v[58:61]
	v_mfma_f32_16x16x32_bf16 v[46:49], v[146:149], v[218:221], v[46:49]
	v_mfma_f32_16x16x32_bf16 v[42:45], v[162:165], v[218:221], v[42:45]
	v_mfma_f32_16x16x32_bf16 v[30:33], v[146:149], v[236:239], v[30:33]
	v_mfma_f32_16x16x32_bf16 v[26:29], v[162:165], v[236:239], v[26:29]
	v_mfma_f32_16x16x32_bf16 v[14:17], v[146:149], v[244:247], v[14:17]
	v_mfma_f32_16x16x32_bf16 v[10:13], v[162:165], v[244:247], v[10:13]
	s_setprio 0
	s_setprio 1
	v_mfma_f32_16x16x32_bf16 v[54:57], v[166:169], v[182:185], v[54:57]
	v_mfma_f32_16x16x32_bf16 v[50:53], v[174:177], v[182:185], v[50:53]
	v_mfma_f32_16x16x32_bf16 v[38:41], v[166:169], v[206:209], v[38:41]
	v_mfma_f32_16x16x32_bf16 v[34:37], v[174:177], v[206:209], v[34:37]
	v_mfma_f32_16x16x32_bf16 v[22:25], v[166:169], v[232:235], v[22:25]
	v_mfma_f32_16x16x32_bf16 v[18:21], v[174:177], v[232:235], v[18:21]
	v_mfma_f32_16x16x32_bf16 v[6:9], v[166:169], v[240:243], v[6:9]
	v_mfma_f32_16x16x32_bf16 v[2:5], v[174:177], v[240:243], v[2:5]
	v_mfma_f32_16x16x32_bf16 v[54:57], v[170:173], v[186:189], v[54:57]
	v_mfma_f32_16x16x32_bf16 v[50:53], v[178:181], v[186:189], v[50:53]
	v_mfma_f32_16x16x32_bf16 v[38:41], v[170:173], v[218:221], v[38:41]
	v_mfma_f32_16x16x32_bf16 v[34:37], v[178:181], v[218:221], v[34:37]
	v_mfma_f32_16x16x32_bf16 v[22:25], v[170:173], v[236:239], v[22:25]
	v_mfma_f32_16x16x32_bf16 v[18:21], v[178:181], v[236:239], v[18:21]
	v_mfma_f32_16x16x32_bf16 v[6:9], v[170:173], v[244:247], v[6:9]
	v_mfma_f32_16x16x32_bf16 v[2:5], v[178:181], v[244:247], v[2:5]
	s_setprio 0
	s_barrier
	s_add_u32 s24, s24, 0x100
	s_addc_u32 s25, s25, 0
	s_cmp_ge_i32 s31, s14
	s_cbranch_scc1 .LBB0_885
	s_branch .LBB0_883
